# speedup vs baseline: 1.0023x; 1.0001x over previous
; template <int MODE, int DQK, bool PIPE = false> ...
;     ...
;   volatile int* sbflag = (volatile int*)(lds + 2 * LDS_STAGE_A);
;   if (MODE == M_SB || MODE == M_FOX) { if (lane == 0) sbflag[w] = 0; }
.LBB0_383:
	s_or_b64 exec, exec, s[6:7]
	v_cmp_eq_u32_e64 s[8:9], 0, v20
	s_and_saveexec_b64 s[6:7], s[8:9]
	s_cbranch_execz .LBB0_385
	s_mov_b64 s[10:11], src_shared_base
	s_lshl_b32 s10, s13, 2
	s_add_i32 s10, s10, 0x10200
	v_mov_b32_e32 v22, s10
	v_mov_b32_e32 v23, s11
	flat_store_dword v[22:23], v0 sc0 sc1
	s_waitcnt lgkmcnt(0)

; template <int MODE, int DQK, bool PIPE = false> ...
;     ...
;     if (MODE == M_FOX) {
;       const float c0 = *(const float*)(st + 32768);
;       const int dn = __all(invl + (cq - c0) * LOG2E - s.m < -40.f) ? 1 : 0;
;       if (lane == 0) sbflag[w] = dn;
;     }
.LBB0_409:
	s_or_b64 exec, exec, s[24:25]
	ds_read_b32 v1, v1 offset:32768
	s_mov_b32 s10, 0xc2200000
	s_mov_b64 s[6:7], exec
	s_waitcnt lgkmcnt(0)
	v_sub_f32_e32 v1, v154, v1
	v_fmamk_f32 v1, v1, 0x3fb8aa3b, v185
	v_sub_f32_e32 v1, v1, v174
	v_cmp_gt_f32_e32 vcc, s10, v1
	s_and_saveexec_b64 s[10:11], s[8:9]
	s_cbranch_execz .LBB0_386
	s_cmp_eq_u64 vcc, s[6:7]
	s_cselect_b64 s[6:7], -1, 0
	v_cndmask_b32_e64 v1, 0, 1, s[6:7]
	v_mov_b64_e32 v[2:3], s[78:79]
	flat_store_dword v[2:3], v1 sc0 sc1
	s_waitcnt lgkmcnt(0)
	s_branch .LBB0_386

; DEV void fs_init(FlashState& s) { s.o[0] = zero16(); s.o[1] = zero16(); s.o[2] = zero16(); s.o[3] = zero16(); s.m = -1e20f; s.l = 0.f; s.R = 0.f; }
; template <int DQK, bool FOX>
; DEV void kv_dma(const bf16_t* __restrict__ Kg, int ldk, const bf16_t* __restrict__ Vtg, int ldv, const float* __restrict__ cumk,
;                 int key0, char* st, int w, int lane) {
;   const unsigned base = (unsigned)(size_t)st;
;   const bf16_t* kb = uni_ptr(Kg + (size_t)key0 * ldk);
;   const bf16_t* vb = uni_ptr(Vtg + key0);
;   if (DQK == 128) {
;     const int r0 = w * 16 + (lane >> 4);
;     const unsigned rowoff = (unsigned)r0 * (unsigned)ldk * 2u;
;     const unsigned pz0 = (unsigned)((lane & 15) ^ (lane >> 4));
; #pragma unroll
;     for (int c = 0; c < 4; ++c)
;       dma16s(kb + (size_t)(4 * c) * ldk, rowoff + ((pz0 ^ (unsigned)(4 * c)) << 4), __builtin_amdgcn_readfirstlane(base + (w * 4 + c) * 1024));
;   } else {
;     const int r0 = w * 16 + (lane >> 3);
; #pragma unroll
;     for (int c = 0; c < 2; ++c) {
;       const int row = r0 + 8 * c;
;       dma16s(kb, (unsigned)row * (unsigned)ldk * 2u + (unsigned)((((lane & 7) ^ ((row >> 1) & 7))) << 4), __builtin_amdgcn_readfirstlane(base + (w * 2 + c) * 1024));
;     }
;   }
;   {
;     const int d0 = w * 32 + (lane >> 3);
; #pragma unroll
;     for (int c = 0; c < 4; ++c) {
;       const int d = d0 + 8 * c;
;       dma16s(vb, (unsigned)d * (unsigned)ldv * 2u + (unsigned)((((lane & 7) ^ ((d >> 1) & 7))) << 4), __builtin_amdgcn_readfirstlane(base + 16384 + (w * 4 + c) * 1024));
;     }
;   }
;   if (FOX) { if (w == 0 && lane < 16) dma16s(uni_ptr(cumk + key0), (unsigned)lane * 16u, __builtin_amdgcn_readfirstlane(base + 32768)); }
; }
; DEV void mha_item(const Params& p, int layer, int mixer, int b, int h, int qt, char* lds) {
;     ...
;     const bf16_t* qp = PR + tokq * PR_LD + PR_QB + h * 128 + hh * 8;
; #pragma unroll
;     for (int ks = 0; ks < 8; ++ks) qf[ks] = *(const bf16x8*)(qp + ks * 16);
;     FlashState s; fs_init(s);
;     flash_loop<M_SB, 128>(s, nullptr, qf, Kbase + PR_KB + h * 128, PR_LD, VT + (size_t)(b * 14 + 2 + h) * 128 * 4096, 4096,
.LBB0_413:
	s_lshl_b32 s24, s23, 7
	s_cmp_eq_u64 s[16:17], 0
	s_cbranch_scc1 .LBB0_427
	v_mov_b64_e32 v[2:3], s[18:19]
	v_mad_u64_u32 v[2:3], s[2:3], v128, s35, v[2:3]
	v_mad_i32_i24 v3, v129, s35, v3
	s_lshl_b32 s28, s24, 1
	v_lshl_add_u64 v[2:3], v[2:3], 0, s[28:29]
	v_lshlrev_b32_e32 v4, 4, v130
	v_mov_b32_e32 v5, v0
	v_lshl_add_u64 v[2:3], v[2:3], 0, v[4:5]
	flat_load_dwordx4 v[96:99], v[2:3] offset:2560
	flat_load_dwordx4 v[100:103], v[2:3] offset:2592
	flat_load_dwordx4 v[104:107], v[2:3] offset:2624
	flat_load_dwordx4 v[108:111], v[2:3] offset:2656
	flat_load_dwordx4 v[112:115], v[2:3] offset:2688
	flat_load_dwordx4 v[116:119], v[2:3] offset:2720
	flat_load_dwordx4 v[120:123], v[2:3] offset:2752
	flat_load_dwordx4 v[124:127], v[2:3] offset:2784
	s_add_u32 s25, s26, s28
	s_mul_i32 s22, s22, 14
	s_addc_u32 s26, s27, 0
	s_add_i32 s23, s23, s22
	s_lshl_b32 s2, s23, 20
	s_add_i32 s2, s2, 0x200000
	v_mov_b32_e32 v2, v192
	s_add_u32 s22, s30, s2
	s_addc_u32 s23, s31, 0
	v_readfirstlane_b32 s2, v2
	s_ashr_i32 s4, s2, 6
	s_flbit_i32_b64 s2, s[16:17]
	s_xor_b32 s6, s2, 63
	s_mul_i32 s2, s6, 0x88000
	s_add_u32 s2, s25, s2
	s_addc_u32 s3, s26, 0
	s_add_u32 s2, s2, 0xe00
	s_addc_u32 s3, s3, 0
	s_lshl_b32 s5, s6, 7
	s_add_u32 s8, s22, s5
	v_bfe_u32 v3, v2, 4, 2
	s_addc_u32 s9, s23, 0
	v_lshl_or_b32 v4, s4, 4, v3
	v_bitop3_b32 v3, v3, v2, 15 bitop3:0x78
	s_lshl_b32 s27, s4, 12
	v_mul_lo_u32 v4, v4, s35
	v_lshlrev_b32_e32 v3, 4, v3
	s_add_u32 s10, s2, 0x8800
	v_or_b32_e32 v138, v4, v3
	s_mov_b32 m0, s27
	s_nop 0
	global_load_lds_dwordx4 v138, s[2:3]
	s_addc_u32 s11, s3, 0
	s_add_i32 s5, s27, 0x400
	v_bitop3_b32 v141, v4, 64, v3 bitop3:0x36
	s_mov_b32 m0, s5
	s_nop 0
	global_load_lds_dwordx4 v141, s[10:11]
	s_add_u32 s10, s2, 0x11000
	s_movk_i32 s5, 0x80
	s_addc_u32 s11, s3, 0
	v_bitop3_b32 v153, v4, s5, v3 bitop3:0x36
	s_add_i32 s5, s27, 0x800
	s_add_u32 s2, s2, 0x19800
	s_mov_b32 m0, s5
	s_nop 0
	global_load_lds_dwordx4 v153, s[10:11]
	s_addc_u32 s3, s3, 0
	s_movk_i32 s5, 0xc0
	v_and_b32_e32 v1, 63, v2
	v_bitop3_b32 v158, v4, s5, v3 bitop3:0x36
	s_add_i32 s5, s27, 0xc00
	s_mov_b32 m0, s5
	s_nop 0
	global_load_lds_dwordx4 v158, s[2:3]
	v_bfe_u32 v3, v2, 3, 3
	v_lshlrev_b32_e32 v4, 4, v2
	s_movk_i32 s3, 0x70
	v_lshl_or_b32 v3, s4, 5, v3
	v_bitop3_b32 v4, v4, s3, v1 bitop3:0x48
	v_lshl_or_b32 v159, v3, 13, v4
	v_or_b32_e32 v4, 8, v3
	v_lshlrev_b32_e32 v5, 13, v4
	v_lshrrev_b32_e32 v4, 1, v4
	v_xor_b32_e32 v4, v4, v2
	v_lshlrev_b32_e32 v4, 4, v4
	v_or_b32_e32 v3, 24, v3
	s_add_i32 s2, s27, 0x4000
	s_mov_b32 m0, s2
	s_nop 0
	global_load_lds_dwordx4 v159, s[8:9]
	v_and_or_b32 v160, v4, s3, v5
	v_lshlrev_b32_e32 v4, 13, v3
	v_lshrrev_b32_e32 v3, 1, v3
	s_add_i32 s2, s27, 0x4400
	s_mov_b32 m0, s2
	s_nop 0
	global_load_lds_dwordx4 v160, s[8:9]
	v_xor_b32_e32 v3, v3, v2
	v_or_b32_e32 v161, 0x20000, v159
	s_add_i32 s2, s27, 0x4800
	s_mov_b32 m0, s2
	s_nop 0
	global_load_lds_dwordx4 v161, s[8:9]
	v_lshlrev_b32_e32 v3, 4, v3
	v_and_or_b32 v162, v3, s3, v4
	s_add_i32 s2, s27, 0x4c00
	s_mov_b32 m0, s2
	s_nop 0
	global_load_lds_dwordx4 v162, s[8:9]
	v_cmp_eq_u32_e64 s[8:9], 0, v1
	s_and_saveexec_b64 s[2:3], s[8:9]
	s_cbranch_execz .LBB0_416
	s_lshl_b32 s5, s4, 2
	s_mov_b64 s[10:11], src_shared_base
	s_add_i32 s5, s5, 0x10200
	v_mov_b32_e32 v4, s5
	v_mov_b32_e32 v5, s11
	flat_store_dword v[4:5], v0 sc0 sc1
	s_waitcnt lgkmcnt(0)

; template <int MODE, int DQK, bool PIPE = false> ...
;     ...
;     if (MODE == M_SB) { const int dn = __all(s.R < -64.f) ? 1 : 0; if (lane == 0) sbflag[w] = dn; }
.LBB0_424:
	s_or_b64 exec, exec, s[82:83]
	s_mov_b32 s12, 0xc2800000
	s_mov_b64 s[6:7], exec
	v_cmp_gt_f32_e32 vcc, s12, v154
	s_and_saveexec_b64 s[12:13], s[8:9]
	s_cbranch_execz .LBB0_417
	s_cmp_eq_u64 vcc, s[6:7]
	s_cselect_b64 s[6:7], -1, 0
	v_cndmask_b32_e64 v1, 0, 1, s[6:7]
	v_mov_b64_e32 v[2:3], s[4:5]
	flat_store_dword v[2:3], v1 sc0 sc1
	s_waitcnt lgkmcnt(0)
	s_branch .LBB0_417
